# c8 + phase 0: rmsnorm row blocks assigned in reverse WG order (17-row waves no longer on the 6-tile WGs)
# baseline (speedup 1.0000x reference)
.LBB0_61:
	s_or_b64 exec, exec, s[2:3]
	s_waitcnt lgkmcnt(0)
	s_sub_i32 s1, s0, s81
	s_add_i32 s1, s1, -1
	s_lshl_b32 s1, s1, 3
	s_add_i32 s2, s80, s1
	s_cmp_gt_i32 s2, 0x80ff
	s_cbranch_scc1 .LBB0_76
	s_ashr_i32 s3, s2, 31
	s_waitcnt lgkmcnt(0)
	s_lshl_b32 s1, s0, 3
	v_lshlrev_b32_e32 v64, 2, v4
	s_lshl_b32 s6, s0, 5
	s_lshl_b32 s22, s0, 4
	s_lshl_b64 s[10:11], s[2:3], 11
	v_mov_b32_e32 v0, s50
	v_mov_b32_e32 v1, s51
	v_ashrrev_i32_e32 v65, 31, v64
	s_add_u32 s10, s78, s10
	v_lshl_add_u64 v[66:67], v[64:65], 2, v[0:1]
	v_lshlrev_b64 v[0:1], 1, v[64:65]
	s_addc_u32 s11, s79, s11
	v_lshl_add_u64 v[2:3], s[78:79], 0, v[0:1]
	s_mov_b64 s[8:9], 0xe671000
	v_lshl_add_u64 v[0:1], s[10:11], 0, v[0:1]
	s_ashr_i32 s7, s6, 31
	v_lshl_add_u64 v[68:69], v[2:3], 0, s[8:9]
	s_mul_i32 s23, s0, 24
	v_lshl_add_u64 v[70:71], v[0:1], 0, s[8:9]
	s_lshl_b64 s[8:9], s[6:7], 11
	v_mov_b32_e32 v72, 0x358637bd
	s_mov_b32 s24, 0x800000
	s_branch .LBB0_64
